# mixer-A main loop: 9 of the 32 row-sum adds per half moved from the QK^T section into the first PV section (VALU balance)
# speedup vs baseline: 1.0008x; 1.0003x over previous
.LBB0_276:
	s_mov_b32 s4, s92
	s_mov_b32 s6, s89
	v_cvt_pk_bf16_f32 v154, v90, v91
	v_lshl_add_u32 v210, s7, 1, v235
	ds_read_b64_tr_b16 v[68:69], v210 offset:24576
	ds_read_b64_tr_b16 v[70:71], v210 offset:25088
	v_add_f32_e32 v67, v98, v99
	v_add_f32_e32 v67, v100, v67
	v_add_f32_e32 v67, v101, v67
	v_add_f32_e32 v67, v102, v67
	v_add_f32_e32 v67, v103, v67
	v_cvt_pk_bf16_f32 v174, v98, v99
	v_cvt_pk_bf16_f32 v175, v100, v101
	s_waitcnt lgkmcnt(9)
	v_mfma_f32_32x32x16_bf16 v[130:145], v[206:209], v[166:169], 0
	ds_read_b64_tr_b16 v[72:73], v210 offset:28672
	ds_read_b64_tr_b16 v[74:75], v210 offset:29184
	v_add_f32_e32 v67, v104, v67
	v_add_f32_e32 v67, v105, v67
	v_add_f32_e32 v67, v106, v67
	v_add_f32_e32 v67, v107, v67
	v_cvt_pk_bf16_f32 v176, v102, v103
	v_cvt_pk_bf16_f32 v177, v104, v105
	s_waitcnt lgkmcnt(10)
	v_mfma_f32_32x32x16_bf16 v[114:129], v[198:201], v[166:169], 0
	ds_read_b64_tr_b16 v[76:77], v210 offset:25600
	ds_read_b64_tr_b16 v[78:79], v210 offset:26112
	v_add_f32_e32 v67, v108, v67
	v_add_f32_e32 v67, v109, v67
	v_add_f32_e32 v67, v110, v67
	v_add_f32_e32 v67, v111, v67
	v_cvt_pk_bf16_f32 v170, v106, v107
	v_cvt_pk_bf16_f32 v171, v108, v109
	s_waitcnt lgkmcnt(11)
	v_mfma_f32_32x32x16_bf16 v[114:129], v[194:197], v[158:161], v[114:129]
	ds_read_b64_tr_b16 v[98:99], v210 offset:29696
	ds_read_b64_tr_b16 v[100:101], v210 offset:30208
	v_add_f32_e32 v67, v112, v67
	v_add_f32_e32 v67, v113, v67
	v_add_f32_e32 v67, v82, v67
	v_add_f32_e32 v67, v83, v67
	v_cvt_pk_bf16_f32 v172, v110, v111
	v_cvt_pk_bf16_f32 v173, v112, v113
	s_waitcnt lgkmcnt(12)
	v_mfma_f32_32x32x16_bf16 v[130:145], v[202:205], v[158:161], v[130:145]
	ds_read_b64_tr_b16 v[102:103], v210 offset:26624
	ds_read_b64_tr_b16 v[104:105], v210 offset:27136
	v_add_f32_e32 v67, v84, v67
	v_add_f32_e32 v67, v85, v67
	v_add_f32_e32 v67, v86, v67
	v_add_f32_e32 v67, v87, v67
	v_cvt_pk_bf16_f32 v162, v82, v83
	v_cvt_pk_bf16_f32 v163, v84, v85
	s_waitcnt lgkmcnt(13)
	v_mfma_f32_32x32x16_bf16 v[130:145], v[190:193], v[150:153], v[130:145]
	ds_read_b64_tr_b16 v[106:107], v210 offset:30720
	ds_read_b64_tr_b16 v[108:109], v210 offset:31232
	v_add_f32_e32 v67, v88, v67
	v_add_f32_e32 v67, v89, v67
	v_cvt_pk_bf16_f32 v164, v86, v87
	v_cvt_pk_bf16_f32 v165, v88, v89
	s_waitcnt lgkmcnt(14)
	v_mfma_f32_32x32x16_bf16 v[114:129], v[186:189], v[150:153], v[114:129]
	ds_read_b64_tr_b16 v[110:111], v210 offset:27648
	ds_read_b64_tr_b16 v[112:113], v210 offset:28160
	s_waitcnt lgkmcnt(14)
	v_mfma_f32_32x32x16_bf16 v[114:129], v[178:181], v[146:149], v[114:129]
	ds_read_b64_tr_b16 v[188:189], v210 offset:31744
	ds_read_b64_tr_b16 v[190:191], v210 offset:32256
	v_mfma_f32_32x32x16_bf16 v[130:145], v[182:185], v[146:149], v[130:145]
	s_add_u32 s8, s2, 0xfffe0000
	s_addc_u32 s9, s3, -1
	s_add_i32 s7, s89, s86
	s_mov_b32 s10, m0
	s_mov_b32 m0, s7
	s_nop 0
	global_load_lds_dwordx4 v222, s[8:9]
	s_mov_b32 m0, s10
	s_add_u32 s8, s0, 0xfffe0000
	s_addc_u32 s9, s1, -1
	s_lshl_b32 s7, s92, 1
	s_add_i32 s7, s7, s87
	s_mov_b32 s10, m0
	s_mov_b32 m0, s7
	s_nop 0
	global_load_lds_dwordx4 v223, s[8:9]
	s_mov_b32 m0, s10
	s_add_u32 s8, s0, 0xfffe0080
	s_addc_u32 s9, s1, -1
	s_addk_i32 s7, 0x2000
	s_mov_b32 s10, m0
	s_mov_b32 m0, s7
	s_nop 0
	global_load_lds_dwordx4 v223, s[8:9]
	s_mov_b32 m0, s10
	v_add_f32_e32 v186, v66, v67
	s_waitcnt lgkmcnt(14)
	v_mfma_f32_32x32x16_bf16 v[2:17], v[174:177], v[68:71], v[2:17]
	v_exp_f32_e32 v130, v130
	v_add_f32_e32 v186, v90, v186
	v_add_f32_e32 v186, v91, v186
	v_add_f32_e32 v186, v92, v186
	v_add_f32_e32 v186, v93, v186
	ds_read_b64_tr_b16 v[192:193], v210 offset:32768
	ds_read_b64_tr_b16 v[194:195], v210 offset:33280
	s_waitcnt lgkmcnt(14)
	v_mfma_f32_32x32x16_bf16 v[18:33], v[174:177], v[72:75], v[18:33]
	v_exp_f32_e32 v131, v131
	v_cvt_pk_bf16_f32 v155, v92, v93
	ds_read_b64_tr_b16 v[90:91], v210 offset:36864
	ds_read_b64_tr_b16 v[92:93], v210 offset:37376
	v_add_u32_e32 v66, s4, v237
	ds_read_b128 v[86:89], v66
	ds_read_b128 v[82:85], v66 offset:512
	s_waitcnt lgkmcnt(14)
	v_mfma_f32_32x32x16_bf16 v[18:33], v[170:173], v[98:101], v[18:33]
	v_exp_f32_e32 v132, v132
	v_cvt_pk_bf16_f32 v156, v94, v95
	v_add_f32_e32 v186, v94, v186
	v_add_f32_e32 v186, v95, v186
	ds_read_b64_tr_b16 v[196:197], v210 offset:33792
	ds_read_b64_tr_b16 v[198:199], v210 offset:34304
	ds_read_b128 v[182:185], v66 offset:2048
	v_mfma_f32_32x32x16_bf16 v[2:17], v[170:173], v[76:79], v[2:17]
	ds_read_b128 v[78:81], v66 offset:2560
	v_exp_f32_e32 v133, v133
	v_cvt_pk_bf16_f32 v157, v96, v97
	v_add_f32_e32 v186, v96, v186
	v_add_f32_e32 v186, v97, v186
	ds_read_b64_tr_b16 v[94:95], v210 offset:37888
	ds_read_b64_tr_b16 v[96:97], v210 offset:38400
	ds_read_b128 v[178:181], v66 offset:4096
	ds_read_b128 v[74:77], v66 offset:4608
	s_waitcnt lgkmcnt(14)
	v_mfma_f32_32x32x16_bf16 v[2:17], v[162:165], v[102:105], v[2:17]
	v_exp_f32_e32 v134, v134
	ds_read_b64_tr_b16 v[98:99], v210 offset:34816
	ds_read_b64_tr_b16 v[100:101], v210 offset:35328
	ds_read_b128 v[70:73], v66 offset:6144
	ds_read_b128 v[66:69], v66 offset:6656
	v_mfma_f32_32x32x16_bf16 v[18:33], v[162:165], v[106:109], v[18:33]
	v_exp_f32_e32 v135, v135
	ds_read_b64_tr_b16 v[102:103], v210 offset:38912
	ds_read_b64_tr_b16 v[104:105], v210 offset:39424
	v_mfma_f32_32x32x16_bf16 v[18:33], v[154:157], v[188:191], v[18:33]
	v_exp_f32_e32 v136, v136
	ds_read_b64_tr_b16 v[106:107], v210 offset:35840
	ds_read_b64_tr_b16 v[108:109], v210 offset:36352
	v_mfma_f32_32x32x16_bf16 v[2:17], v[154:157], v[110:113], v[2:17]
	v_exp_f32_e32 v137, v137
	ds_read_b64_tr_b16 v[110:111], v210 offset:39936
	ds_read_b64_tr_b16 v[112:113], v210 offset:40448
	s_waitcnt lgkmcnt(14)
	v_mfma_f32_32x32x16_bf16 v[34:49], v[174:177], v[192:195], v[34:49]
	v_exp_f32_e32 v138, v138
	v_exp_f32_e32 v114, v114
	v_exp_f32_e32 v115, v115
	v_mfma_f32_32x32x16_bf16 v[50:65], v[174:177], v[90:93], v[50:65]
	v_exp_f32_e32 v139, v139
	v_exp_f32_e32 v116, v116
	v_exp_f32_e32 v117, v117
	v_mfma_f32_32x32x16_bf16 v[34:49], v[170:173], v[196:199], v[34:49]
	v_exp_f32_e32 v140, v140
	v_exp_f32_e32 v118, v118
	v_exp_f32_e32 v119, v119
	s_waitcnt lgkmcnt(12)
	v_mfma_f32_32x32x16_bf16 v[50:65], v[170:173], v[94:97], v[50:65]
	v_exp_f32_e32 v141, v141
	v_exp_f32_e32 v120, v120
	v_exp_f32_e32 v121, v121
	s_waitcnt lgkmcnt(8)
	v_mfma_f32_32x32x16_bf16 v[34:49], v[162:165], v[98:101], v[34:49]
	v_exp_f32_e32 v142, v142
	v_exp_f32_e32 v122, v122
	v_exp_f32_e32 v123, v123
	s_waitcnt lgkmcnt(4)
	v_mfma_f32_32x32x16_bf16 v[50:65], v[162:165], v[102:105], v[50:65]
	v_exp_f32_e32 v143, v143
	v_exp_f32_e32 v124, v124
	v_exp_f32_e32 v125, v125
	s_waitcnt lgkmcnt(2)
	v_mfma_f32_32x32x16_bf16 v[34:49], v[154:157], v[106:109], v[34:49]
	v_exp_f32_e32 v144, v144
	v_exp_f32_e32 v126, v126
	v_exp_f32_e32 v127, v127
	s_waitcnt lgkmcnt(0)
	v_mfma_f32_32x32x16_bf16 v[50:65], v[154:157], v[110:113], v[50:65]
	v_exp_f32_e32 v145, v145
	v_exp_f32_e32 v128, v128
	v_exp_f32_e32 v129, v129
	s_waitcnt vmcnt(3) lgkmcnt(0)
	s_barrier
	s_add_i32 s7, s92, 0x2000
	s_cmpk_lg_i32 s92, 0x4000
	s_cselect_b32 s89, s7, 0
	v_lshl_add_u32 v210, s6, 1, v235
	ds_read_b64_tr_b16 v[188:189], v210 offset:24576
	ds_read_b64_tr_b16 v[190:191], v210 offset:25088
	v_mfma_f32_32x32x16_bf16 v[98:113], v[86:89], v[166:169], 0
	v_add_f32_e32 v90, v130, v131
	v_add_f32_e32 v90, v132, v90
	v_add_f32_e32 v90, v133, v90
	v_add_f32_e32 v90, v134, v90
	v_add_f32_e32 v90, v135, v90
	v_cvt_pk_bf16_f32 v174, v130, v131
	v_cvt_pk_bf16_f32 v175, v132, v133
	ds_read_b64_tr_b16 v[130:131], v210 offset:28672
	ds_read_b64_tr_b16 v[132:133], v210 offset:29184
	v_add_f32_e32 v86, v136, v90
	v_add_f32_e32 v86, v137, v86
	v_add_f32_e32 v86, v138, v86
	v_add_f32_e32 v154, v139, v86
	v_mfma_f32_32x32x16_bf16 v[82:97], v[82:85], v[166:169], 0
	v_cvt_pk_bf16_f32 v176, v134, v135
	v_cvt_pk_bf16_f32 v177, v136, v137
	ds_read_b64_tr_b16 v[134:135], v210 offset:25600
	ds_read_b64_tr_b16 v[136:137], v210 offset:26112
	v_mfma_f32_32x32x16_bf16 v[82:97], v[78:81], v[158:161], v[82:97]
	v_add_f32_e32 v154, v140, v154
	v_add_f32_e32 v154, v141, v154
	v_add_f32_e32 v154, v142, v154
	v_add_f32_e32 v154, v143, v154
	v_cvt_pk_bf16_f32 v170, v138, v139
	v_cvt_pk_bf16_f32 v171, v140, v141
	ds_read_b64_tr_b16 v[138:139], v210 offset:29696
	ds_read_b64_tr_b16 v[140:141], v210 offset:30208
	v_mfma_f32_32x32x16_bf16 v[98:113], v[182:185], v[158:161], v[98:113]
	v_add_f32_e32 v78, v144, v154
	v_add_f32_e32 v78, v145, v78
	v_add_f32_e32 v78, v114, v78
	v_add_f32_e32 v154, v115, v78
	v_cvt_pk_bf16_f32 v172, v142, v143
	v_cvt_pk_bf16_f32 v173, v144, v145
	ds_read_b64_tr_b16 v[78:79], v210 offset:26624
	ds_read_b64_tr_b16 v[80:81], v210 offset:27136
	v_mfma_f32_32x32x16_bf16 v[98:113], v[178:181], v[150:153], v[98:113]
	v_add_f32_e32 v142, v116, v154
	v_add_f32_e32 v142, v117, v142
	v_add_f32_e32 v142, v118, v142
	v_add_f32_e32 v142, v119, v142
	v_cvt_pk_bf16_f32 v162, v114, v115
	v_cvt_pk_bf16_f32 v163, v116, v117
	ds_read_b64_tr_b16 v[114:115], v210 offset:30720
	ds_read_b64_tr_b16 v[116:117], v210 offset:31232
	v_mfma_f32_32x32x16_bf16 v[82:97], v[74:77], v[150:153], v[82:97]
	v_add_f32_e32 v74, v120, v142
	v_add_f32_e32 v142, v121, v74
	v_cvt_pk_bf16_f32 v164, v118, v119
	v_cvt_pk_bf16_f32 v165, v120, v121
	ds_read_b64_tr_b16 v[74:75], v210 offset:27648
	ds_read_b64_tr_b16 v[76:77], v210 offset:28160
	v_mfma_f32_32x32x16_bf16 v[82:97], v[66:69], v[146:149], v[82:97]
	v_mfma_f32_32x32x16_bf16 v[98:113], v[70:73], v[146:149], v[98:113]
	ds_read_b64_tr_b16 v[70:71], v210 offset:31744
	ds_read_b64_tr_b16 v[72:73], v210 offset:32256
	s_add_i32 s6, s92, s86
	s_mov_b32 s7, m0
	s_mov_b32 m0, s6
	s_nop 0
	global_load_lds_dwordx4 v222, s[2:3]
	s_mov_b32 m0, s7
	s_lshl_b32 s6, s89, 1
	s_add_i32 s76, s76, 2
	s_add_i32 s8, s6, s87
	s_mov_b32 s6, m0
	s_mov_b32 m0, s8
	s_nop 0
	global_load_lds_dwordx4 v223, s[0:1]
	s_mov_b32 m0, s6
	s_add_u32 s6, s0, 0x80
	s_addc_u32 s7, s1, 0
	s_addk_i32 s8, 0x2000
	s_mov_b32 s9, m0
	s_mov_b32 m0, s8
	s_nop 0
	global_load_lds_dwordx4 v223, s[6:7]
	s_mov_b32 m0, s9
	v_add_f32_e32 v66, v186, v142
	s_waitcnt lgkmcnt(14)
	v_mfma_f32_32x32x16_bf16 v[2:17], v[174:177], v[188:191], v[2:17]
	v_exp_f32_e32 v98, v98
	v_cvt_pk_bf16_f32 v154, v122, v123
	v_add_f32_e32 v66, v122, v66
	v_add_f32_e32 v66, v123, v66
	v_add_f32_e32 v66, v124, v66
	v_add_f32_e32 v66, v125, v66
	ds_read_b64_tr_b16 v[118:119], v210 offset:32768
	ds_read_b64_tr_b16 v[120:121], v210 offset:33280
	s_waitcnt lgkmcnt(14)
	v_mfma_f32_32x32x16_bf16 v[18:33], v[174:177], v[130:133], v[18:33]
	v_exp_f32_e32 v99, v99
	v_cvt_pk_bf16_f32 v155, v124, v125
	ds_read_b64_tr_b16 v[122:123], v210 offset:36864
	ds_read_b64_tr_b16 v[124:125], v210 offset:37376
	v_add_u32_e32 v67, s89, v237
	ds_read_b128 v[206:209], v67
	ds_read_b128 v[198:201], v67 offset:512
	s_waitcnt lgkmcnt(14)
	v_mfma_f32_32x32x16_bf16 v[18:33], v[170:173], v[138:141], v[18:33]
	v_exp_f32_e32 v100, v100
	v_cvt_pk_bf16_f32 v156, v126, v127
	v_add_f32_e32 v66, v126, v66
	v_add_f32_e32 v66, v127, v66
	ds_read_b64_tr_b16 v[130:131], v210 offset:33792
	ds_read_b64_tr_b16 v[132:133], v210 offset:34304
	ds_read_b128 v[202:205], v67 offset:2048
	ds_read_b128 v[194:197], v67 offset:2560
	v_mfma_f32_32x32x16_bf16 v[2:17], v[170:173], v[134:137], v[2:17]
	v_exp_f32_e32 v101, v101
	v_cvt_pk_bf16_f32 v157, v128, v129
	v_add_f32_e32 v66, v128, v66
	v_add_f32_e32 v66, v129, v66
	ds_read_b64_tr_b16 v[126:127], v210 offset:37888
	ds_read_b64_tr_b16 v[128:129], v210 offset:38400
	ds_read_b128 v[190:193], v67 offset:4096
	ds_read_b128 v[186:189], v67 offset:4608
	s_waitcnt lgkmcnt(14)
	v_mfma_f32_32x32x16_bf16 v[2:17], v[162:165], v[78:81], v[2:17]
	v_exp_f32_e32 v102, v102
	ds_read_b64_tr_b16 v[78:79], v210 offset:34816
	ds_read_b64_tr_b16 v[80:81], v210 offset:35328
	ds_read_b128 v[182:185], v67 offset:6144
	ds_read_b128 v[178:181], v67 offset:6656
	v_mfma_f32_32x32x16_bf16 v[18:33], v[162:165], v[114:117], v[18:33]
	v_exp_f32_e32 v103, v103
	ds_read_b64_tr_b16 v[114:115], v210 offset:38912
	ds_read_b64_tr_b16 v[116:117], v210 offset:39424
	v_mfma_f32_32x32x16_bf16 v[18:33], v[154:157], v[70:73], v[18:33]
	v_exp_f32_e32 v104, v104
	v_mfma_f32_32x32x16_bf16 v[2:17], v[154:157], v[74:77], v[2:17]
	ds_read_b64_tr_b16 v[74:75], v210 offset:35840
	ds_read_b64_tr_b16 v[76:77], v210 offset:36352
	v_exp_f32_e32 v105, v105
	ds_read_b64_tr_b16 v[68:69], v210 offset:39936
	ds_read_b64_tr_b16 v[70:71], v210 offset:40448
	s_waitcnt lgkmcnt(14)
	v_mfma_f32_32x32x16_bf16 v[34:49], v[174:177], v[118:121], v[34:49]
	v_exp_f32_e32 v106, v106
	v_exp_f32_e32 v82, v82
	v_exp_f32_e32 v83, v83
	v_mfma_f32_32x32x16_bf16 v[50:65], v[174:177], v[122:125], v[50:65]
	v_exp_f32_e32 v107, v107
	v_exp_f32_e32 v84, v84
	v_exp_f32_e32 v85, v85
	v_mfma_f32_32x32x16_bf16 v[34:49], v[170:173], v[130:133], v[34:49]
	v_exp_f32_e32 v108, v108
	v_exp_f32_e32 v86, v86
	v_exp_f32_e32 v87, v87
	s_waitcnt lgkmcnt(12)
	v_mfma_f32_32x32x16_bf16 v[50:65], v[170:173], v[126:129], v[50:65]
	v_exp_f32_e32 v109, v109
	v_exp_f32_e32 v88, v88
	v_exp_f32_e32 v89, v89
	s_waitcnt lgkmcnt(8)
	v_mfma_f32_32x32x16_bf16 v[34:49], v[162:165], v[78:81], v[34:49]
	v_exp_f32_e32 v110, v110
	v_exp_f32_e32 v90, v90
	v_exp_f32_e32 v91, v91
	s_waitcnt lgkmcnt(4)
	v_mfma_f32_32x32x16_bf16 v[50:65], v[162:165], v[114:117], v[50:65]
	v_exp_f32_e32 v111, v111
	v_exp_f32_e32 v92, v92
	v_exp_f32_e32 v93, v93
	s_waitcnt lgkmcnt(2)
	v_mfma_f32_32x32x16_bf16 v[34:49], v[154:157], v[74:77], v[34:49]
	v_exp_f32_e32 v112, v112
	v_exp_f32_e32 v94, v94
	v_exp_f32_e32 v95, v95
	s_waitcnt lgkmcnt(0)
	v_mfma_f32_32x32x16_bf16 v[50:65], v[154:157], v[68:71], v[50:65]
	v_exp_f32_e32 v113, v113
	v_exp_f32_e32 v96, v96
	v_exp_f32_e32 v97, v97
	s_add_i32 s6, s89, 0x2000
	s_cmpk_lg_i32 s89, 0x4000
	s_cselect_b32 s92, s6, 0
	s_add_u32 s0, s0, 0x40000
	s_addc_u32 s1, s1, 0
	s_waitcnt vmcnt(3) lgkmcnt(0)
	s_barrier
	s_add_u32 s2, s2, 0x40000
	s_addc_u32 s3, s3, 0
	s_cmp_ge_i32 s76, s5
	s_mov_b32 s7, s4
	s_cbranch_scc0 .LBB0_276
	s_branch .LBB0_278
